# grid barrier: the last arriver of an XCD issues the releasing generation bump before its own L1 invalidate instead of behind it
# baseline (speedup 1.0000x reference)
; DI unsigned xb_add(unsigned* p, unsigned v) { return __hip_atomic_fetch_add(p, v, __ATOMIC_RELAXED, __HIP_MEMORY_SCOPE_AGENT); }
; DI void xcd_barrier(const XcdBarrier& b) {
;     ...
;             __builtin_amdgcn_fence(__ATOMIC_ACQUIRE, "agent");
;             xb_add(&bar[XB_XGEN(b.x)], 1u);
;             asm volatile("s_waitcnt vmcnt(0)" ::: "memory");
.LBB0_402:
	s_or_b64 exec, exec, s[6:7]
	s_mov_b64 s[6:7], exec
	v_mbcnt_lo_u32_b32 v0, s6, 0
	v_mbcnt_hi_u32_b32 v0, s7, v0
	v_cmp_eq_u32_e32 vcc, 0, v0
	s_waitcnt vmcnt(0)
	s_and_saveexec_b64 s[8:9], vcc
	s_cbranch_execz .LBB0_404
	s_bcnt1_i32_b64 s6, s[6:7]
	v_mov_b32_e32 v0, s6
	v_readlane_b32 s6, v255, 11
	v_readlane_b32 s7, v255, 12
	s_nop 4
	global_atomic_add v193, v0, s[6:7]
.LBB0_404:
	s_or_b64 exec, exec, s[8:9]
	buffer_inv sc1
	s_waitcnt vmcnt(0)
